# row phases: the bf16 row stores are write-through (sc1), so less freshly dirtied L2 data is left for the barrier's write-back
# baseline (speedup 1.0000x reference)
.LBB0_542:
	s_or_b64 exec, exec, s[0:1]
	s_and_b64 vcc, exec, s[38:39]
	v_ashrrev_i32_e32 v133, 31, v132
	s_cbranch_vccnz .LBB0_551
	v_lshlrev_b32_e32 v142, 16, v72
	v_and_b32_e32 v143, 0xffff0000, v72
	v_lshlrev_b32_e32 v94, 16, v84
	v_and_b32_e32 v95, 0xffff0000, v84
	v_lshlrev_b32_e32 v92, 16, v85
	v_and_b32_e32 v93, 0xffff0000, v85
	v_lshlrev_b32_e32 v90, 16, v86
	v_and_b32_e32 v91, 0xffff0000, v86
	v_lshlrev_b32_e32 v84, 16, v87
	v_and_b32_e32 v85, 0xffff0000, v87
	v_lshlrev_b32_e32 v72, 16, v73
	v_and_b32_e32 v73, 0xffff0000, v73
	v_pk_mul_f32 v[86:87], v[142:143], v[142:143]
	v_pk_mul_f32 v[146:147], v[72:73], v[72:73]
	v_add_f32_e32 v86, v86, v87
	v_lshlrev_b32_e32 v144, 16, v74
	v_and_b32_e32 v145, 0xffff0000, v74
	v_add_f32_e32 v86, v146, v86
	v_pk_mul_f32 v[148:149], v[144:145], v[144:145]
	v_add_f32_e32 v86, v147, v86
	v_lshlrev_b32_e32 v74, 16, v75
	v_and_b32_e32 v75, 0xffff0000, v75
	v_add_f32_e32 v86, v148, v86
	v_pk_mul_f32 v[150:151], v[74:75], v[74:75]
	v_add_f32_e32 v86, v149, v86
	v_add_f32_e32 v86, v150, v86
	v_pk_mul_f32 v[152:153], v[94:95], v[94:95]
	v_add_f32_e32 v86, v151, v86
	v_add_f32_e32 v86, v152, v86
	v_pk_mul_f32 v[154:155], v[92:93], v[92:93]
	v_add_f32_e32 v86, v153, v86
	v_add_f32_e32 v86, v154, v86
	v_pk_mul_f32 v[156:157], v[90:91], v[90:91]
	v_add_f32_e32 v86, v155, v86
	v_add_f32_e32 v86, v156, v86
	v_add_u32_e32 v87, 64, v237
	v_pk_mul_f32 v[158:159], v[84:85], v[84:85]
	v_add_f32_e32 v86, v157, v86
	v_add_f32_e32 v86, v158, v86
	v_add_f32_e32 v86, v159, v86
	s_mov_b32 s0, 0xf800000
	v_readlane_b32 s4, v254, 24
	v_readlane_b32 s5, v254, 25
	s_nop 1
	v_add_f32_dpp v86, v86, v86 row_shr:1 row_mask:0xf bank_mask:0xf
	s_nop 1
	v_add_f32_dpp v86, v86, v86 row_shr:2 row_mask:0xf bank_mask:0xf
	s_nop 1
	v_add_f32_dpp v86, v86, v86 row_shr:4 row_mask:0xf bank_mask:0xf
	s_nop 1
	v_add_f32_dpp v86, v86, v86 row_shr:8 row_mask:0xf bank_mask:0xf
	s_nop 1
	v_add_f32_dpp v86, v86, v86 row_bcast:15 row_mask:0xa bank_mask:0xf
	s_nop 1
	v_add_f32_dpp v86, v86, v86 row_bcast:31 row_mask:0xc bank_mask:0xf
	s_nop 1
	v_readlane_b32 s32, v86, 63
	s_nop 1
	v_mov_b32_e32 v86, s32
	v_fmamk_f32 v86, v86, 0x3a800000, v225
	v_mul_f32_e32 v87, 0x4f800000, v86
	v_cmp_gt_f32_e32 vcc, s0, v86
	s_nop 1
	v_cndmask_b32_e32 v86, v86, v87, vcc
	v_sqrt_f32_e32 v87, v86
	s_nop 0
	v_add_u32_e32 v89, -1, v87
	v_fma_f32 v112, -v89, v87, v86
	v_cmp_ge_f32_e64 s[44:45], 0, v112
	v_add_u32_e32 v112, 1, v87
	s_nop 0
	v_cndmask_b32_e64 v89, v87, v89, s[44:45]
	v_fma_f32 v87, -v112, v87, v86
	v_cmp_lt_f32_e64 s[44:45], 0, v87
	s_nop 1
	v_cndmask_b32_e64 v87, v89, v112, s[44:45]
	v_mul_f32_e32 v89, 0x37800000, v87
	v_cndmask_b32_e32 v87, v87, v89, vcc
	v_cmp_class_f32_e32 vcc, v86, v226
	s_nop 1
	v_cndmask_b32_e32 v86, v87, v86, vcc
	v_div_scale_f32 v87, s[0:1], v86, v86, 1.0
	v_rcp_f32_e32 v89, v87
	s_mov_b64 s[0:1], -1
	v_fma_f32 v112, -v87, v89, 1.0
	v_fmac_f32_e32 v89, v112, v89
	v_div_scale_f32 v112, vcc, 1.0, v86, 1.0
	v_mul_f32_e32 v141, v112, v89
	v_fma_f32 v146, -v87, v141, v112
	v_fmac_f32_e32 v141, v146, v89
	v_fma_f32 v87, -v87, v141, v112
	v_div_fmas_f32 v87, v87, v89, v141
	v_div_fixup_f32 v86, v87, v86, 1.0
	v_pk_mul_f32 v[72:73], v[86:87], v[72:73] op_sel_hi:[0,1]
	v_pk_fma_f32 v[38:39], v[102:103], v[72:73], v[38:39]
	v_pk_mul_f32 v[72:73], v[86:87], v[144:145] op_sel_hi:[0,1]
	v_pk_fma_f32 v[32:33], v[106:107], v[72:73], v[32:33]
	v_pk_mul_f32 v[72:73], v[86:87], v[74:75] op_sel_hi:[0,1]
	v_pk_mul_f32 v[142:143], v[86:87], v[142:143] op_sel_hi:[0,1]
	v_pk_fma_f32 v[34:35], v[110:111], v[72:73], v[34:35]
	v_lshlrev_b64 v[72:73], 11, v[132:133]
	v_pk_fma_f32 v[36:37], v[98:99], v[142:143], v[36:37]
	v_lshl_add_u64 v[74:75], v[114:115], 0, v[72:73]
	s_and_b64 vcc, exec, s[4:5]
	s_cbranch_vccz .LBB0_545
	v_cvt_pk_bf16_f32 v142, v36, v37
	v_cvt_pk_bf16_f32 v143, v38, v39
	v_cvt_pk_bf16_f32 v144, v32, v33
	v_cvt_pk_bf16_f32 v145, v34, v35
	global_store_dwordx4 v[74:75], v[142:145], off sc1
	s_mov_b64 s[0:1], 0

.LBB0_547:
	v_mov_b32_e32 v87, v86
	v_readlane_b32 s0, v254, 24
	v_pk_mul_f32 v[94:95], v[86:87], v[94:95]
	v_pk_mul_f32 v[92:93], v[86:87], v[92:93]
	v_pk_mul_f32 v[90:91], v[86:87], v[90:91]
	v_pk_mul_f32 v[84:85], v[86:87], v[84:85]
	v_readlane_b32 s1, v254, 25
	v_pk_fma_f32 v[44:45], v[118:119], v[94:95], v[44:45]
	v_pk_fma_f32 v[46:47], v[122:123], v[92:93], v[46:47]
	v_pk_fma_f32 v[40:41], v[126:127], v[90:91], v[40:41]
	v_pk_fma_f32 v[42:43], v[130:131], v[84:85], v[42:43]
	s_andn2_b64 vcc, exec, s[0:1]
	s_mov_b64 s[0:1], -1
	s_cbranch_vccnz .LBB0_549
	v_cvt_pk_bf16_f32 v84, v44, v45
	v_cvt_pk_bf16_f32 v85, v46, v47
	v_cvt_pk_bf16_f32 v86, v40, v41
	v_cvt_pk_bf16_f32 v87, v42, v43
	s_mov_b64 s[0:1], 0
	global_store_dwordx4 v[74:75], v[84:87], off offset:1024 sc1

.LBB0_551:
	s_andn2_b64 vcc, exec, s[14:15]
	s_cbranch_vccnz .LBB0_553
	v_lshlrev_b64 v[72:73], 11, v[132:133]
	v_lshl_add_u64 v[84:85], v[114:115], 0, v[72:73]
	v_cvt_pk_bf16_f32 v72, v36, v37
	v_cvt_pk_bf16_f32 v73, v38, v39
	v_cvt_pk_bf16_f32 v74, v32, v33
	v_cvt_pk_bf16_f32 v75, v34, v35
	global_store_dwordx4 v[84:85], v[72:75], off sc1
	s_nop 1
	v_cvt_pk_bf16_f32 v72, v44, v45
	v_cvt_pk_bf16_f32 v73, v46, v47
	v_cvt_pk_bf16_f32 v74, v40, v41
	v_cvt_pk_bf16_f32 v75, v42, v43
	global_store_dwordx4 v[84:85], v[72:75], off offset:1024 sc1
.LBB0_553:
	s_and_b64 vcc, exec, s[40:41]
	s_cbranch_vccnz .LBB0_526
	v_mul_f32_e32 v74, v37, v37
	v_fmac_f32_e32 v74, v36, v36
	v_fmac_f32_e32 v74, v38, v38
	v_fmac_f32_e32 v74, v39, v39
	v_fmac_f32_e32 v74, v32, v32
	v_fmac_f32_e32 v74, v33, v33
	v_fmac_f32_e32 v74, v34, v34
	v_fmac_f32_e32 v74, v35, v35
	v_fmac_f32_e32 v74, v44, v44
	v_fmac_f32_e32 v74, v45, v45
	v_fmac_f32_e32 v74, v46, v46
	v_fmac_f32_e32 v74, v47, v47
	v_fmac_f32_e32 v74, v40, v40
	v_fmac_f32_e32 v74, v41, v41
	v_pk_mul_f32 v[72:73], v[42:43], v[42:43]
	s_mov_b32 s0, 0xf800000
	v_add_f32_e32 v72, v72, v74
	v_add_f32_e32 v72, v73, v72
	v_add_u32_e32 v73, 64, v237
	s_nop 1
	v_add_f32_dpp v72, v72, v72 row_shr:1 row_mask:0xf bank_mask:0xf
	s_nop 1
	v_add_f32_dpp v72, v72, v72 row_shr:2 row_mask:0xf bank_mask:0xf
	s_nop 1
	v_add_f32_dpp v72, v72, v72 row_shr:4 row_mask:0xf bank_mask:0xf
	s_nop 1
	v_add_f32_dpp v72, v72, v72 row_shr:8 row_mask:0xf bank_mask:0xf
	s_nop 1
	v_add_f32_dpp v72, v72, v72 row_bcast:15 row_mask:0xa bank_mask:0xf
	s_nop 1
	v_add_f32_dpp v72, v72, v72 row_bcast:31 row_mask:0xc bank_mask:0xf
	s_nop 1
	v_readlane_b32 s32, v72, 63
	s_nop 1
	v_mov_b32_e32 v72, s32
	v_fmamk_f32 v72, v72, 0x3a800000, v225
	v_mul_f32_e32 v73, 0x4f800000, v72
	v_cmp_gt_f32_e32 vcc, s0, v72
	s_nop 1
	v_cndmask_b32_e32 v72, v72, v73, vcc
	v_sqrt_f32_e32 v73, v72
	s_nop 0
	v_add_u32_e32 v74, -1, v73
	v_fma_f32 v75, -v74, v73, v72
	v_cmp_ge_f32_e64 s[44:45], 0, v75
	v_add_u32_e32 v75, 1, v73
	s_nop 0
	v_cndmask_b32_e64 v74, v73, v74, s[44:45]
	v_fma_f32 v73, -v75, v73, v72
	v_cmp_lt_f32_e64 s[44:45], 0, v73
	s_nop 1
	v_cndmask_b32_e64 v73, v74, v75, s[44:45]
	v_mul_f32_e32 v74, 0x37800000, v73
	v_cndmask_b32_e32 v73, v73, v74, vcc
	v_cmp_class_f32_e32 vcc, v72, v226
	s_nop 1
	v_cndmask_b32_e32 v72, v73, v72, vcc
	v_div_scale_f32 v73, s[0:1], v72, v72, 1.0
	v_rcp_f32_e32 v74, v73
	s_nop 0
	v_fma_f32 v75, -v73, v74, 1.0
	v_fmac_f32_e32 v74, v75, v74
	v_div_scale_f32 v75, vcc, 1.0, v72, 1.0
	v_mul_f32_e32 v84, v75, v74
	v_fma_f32 v85, -v73, v84, v75
	v_fmac_f32_e32 v84, v85, v74
	v_fma_f32 v73, -v73, v84, v75
	v_div_fmas_f32 v73, v73, v74, v84
	v_div_fixup_f32 v72, v73, v72, 1.0
	v_pk_mul_f32 v[36:37], v[36:37], v[72:73] op_sel_hi:[1,0]
	v_pk_mul_f32 v[38:39], v[38:39], v[72:73] op_sel_hi:[1,0]
	v_pk_mul_f32 v[32:33], v[32:33], v[72:73] op_sel_hi:[1,0]
	v_pk_mul_f32 v[36:37], v[96:97], v[36:37]
	v_pk_mul_f32 v[38:39], v[100:101], v[38:39]
	v_pk_mul_f32 v[32:33], v[104:105], v[32:33]
	v_cvt_pk_bf16_f32 v36, v36, v37
	v_cvt_pk_bf16_f32 v37, v38, v39
	v_cvt_pk_bf16_f32 v38, v32, v33
	v_pk_mul_f32 v[32:33], v[34:35], v[72:73] op_sel_hi:[1,0]
	v_lshlrev_b64 v[74:75], 11, v[132:133]
	v_pk_mul_f32 v[32:33], v[108:109], v[32:33]
	v_pk_mul_f32 v[34:35], v[46:47], v[72:73] op_sel_hi:[1,0]
	v_cvt_pk_bf16_f32 v39, v32, v33
	v_pk_mul_f32 v[32:33], v[44:45], v[72:73] op_sel_hi:[1,0]
	v_lshl_add_u64 v[74:75], v[138:139], 0, v[74:75]
	v_pk_mul_f32 v[32:33], v[116:117], v[32:33]
	v_pk_mul_f32 v[34:35], v[120:121], v[34:35]
	global_store_dwordx4 v[74:75], v[36:39], off sc1
	v_cvt_pk_bf16_f32 v32, v32, v33
	v_cvt_pk_bf16_f32 v33, v34, v35
	v_pk_mul_f32 v[34:35], v[40:41], v[72:73] op_sel_hi:[1,0]
	v_pk_mul_f32 v[36:37], v[42:43], v[72:73] op_sel_hi:[1,0]
	v_pk_mul_f32 v[34:35], v[124:125], v[34:35]
	v_pk_mul_f32 v[36:37], v[128:129], v[36:37]
	v_cvt_pk_bf16_f32 v34, v34, v35
	v_cvt_pk_bf16_f32 v35, v36, v37
	global_store_dwordx4 v[74:75], v[32:35], off offset:1024 sc1
	s_branch .LBB0_526
